# dead ds_bpermute address recomputation removed from the rmsnorm loop and m3 tail
# baseline (speedup 1.0000x reference)
.LBB0_84:
	global_load_dwordx4 v[20:23], v[18:19], off offset:-3072
	global_load_dwordx4 v[24:27], v[18:19], off offset:-2048
	global_load_dwordx4 v[28:31], v[18:19], off offset:-1024
	global_load_dwordx4 v[32:35], v[18:19], off
	s_add_i32 s2, s2, s78
	v_lshl_add_u64 v[18:19], v[18:19], 0, s[6:7]
	s_cmpk_lt_i32 s2, 0x4000
	s_waitcnt vmcnt(3)
	v_pk_mul_f32 v[36:37], v[22:23], v[22:23]
	v_pk_mul_f32 v[38:39], v[20:21], v[20:21]
	s_waitcnt vmcnt(2)
	v_pk_mul_f32 v[40:41], v[26:27], v[26:27]
	v_pk_mul_f32 v[42:43], v[24:25], v[24:25]
	v_pk_mov_b32 v[48:49], v[38:39], v[36:37] op_sel:[1,0]
	v_mov_b32_e32 v39, v37
	v_pk_mov_b32 v[36:37], v[42:43], v[40:41] op_sel:[1,0]
	v_mov_b32_e32 v43, v41
	s_waitcnt vmcnt(1)
	v_mul_f32_e32 v44, v29, v29
	v_mul_f32_e32 v46, v31, v31
	v_pk_add_f32 v[38:39], v[48:49], v[38:39]
	v_pk_add_f32 v[36:37], v[36:37], v[42:43]
	s_waitcnt vmcnt(0)
	v_mul_f32_e32 v55, v32, v32
	v_mul_f32_e32 v56, v33, v33
	v_mul_f32_e32 v57, v34, v34
	v_mul_f32_e32 v58, v35, v35
	v_pk_fma_f32 v[40:41], v[28:29], v[28:29], v[44:45] op_sel_hi:[1,1,0]
	v_pk_fma_f32 v[44:45], v[30:31], v[30:31], v[46:47] op_sel_hi:[1,1,0]
	v_pk_add_f32 v[38:39], v[38:39], v[38:39] op_sel:[0,1] op_sel_hi:[1,0]
	v_pk_add_f32 v[36:37], v[36:37], v[36:37] op_sel:[0,1] op_sel_hi:[1,0]
	v_mov_b32_e32 v41, v57
	v_mov_b32_e32 v45, v58
	v_mov_b32_e32 v39, v55
	v_mov_b32_e32 v37, v56
	v_pk_add_f32 v[40:41], v[40:41], v[44:45]
	v_pk_add_f32 v[36:37], v[38:39], v[36:37]
	s_nop 0
	v_pk_add_f32 v[36:37], v[36:37], v[40:41]
	s_nop 0
	v_add_f32_e32 v36, v36, v37
	s_nop 1
	v_add_f32_dpp v37, v36, v36 quad_perm:[1,0,3,2] row_mask:0xf bank_mask:0xf
	s_nop 1
	v_add_f32_dpp v36, v37, v37 quad_perm:[2,3,0,1] row_mask:0xf bank_mask:0xf
	s_nop 1
	v_add_f32_dpp v37, v36, v36 row_half_mirror row_mask:0xf bank_mask:0xf
	s_nop 1
	v_add_f32_dpp v36, v37, v37 row_mirror row_mask:0xf bank_mask:0xf
	s_nop 1
	v_add_f32_dpp v36, v36, v36 row_bcast:15 row_mask:0xa bank_mask:0xf
	s_nop 1
	v_add_f32_dpp v36, v36, v36 row_bcast:31 row_mask:0xc bank_mask:0xf
	s_nop 1
	v_readlane_b32 s90, v36, 63
	s_nop 1
	v_mov_b32_e32 v36, s90
	v_fmamk_f32 v36, v36, 0x3a800000, v195
	v_mul_f32_e32 v37, 0x4b800000, v36
	v_cmp_gt_f32_e32 vcc, s67, v36
	s_nop 1
	v_cndmask_b32_e32 v36, v36, v37, vcc
	v_rsq_f32_e32 v36, v36
	s_nop 0
	v_mul_f32_e32 v37, 0x45800000, v36
	v_cndmask_b32_e32 v36, v36, v37, vcc
	v_pk_mul_f32 v[20:21], v[20:21], v[36:37] op_sel_hi:[1,0]
	v_pk_mul_f32 v[22:23], v[22:23], v[36:37] op_sel_hi:[1,0]
	v_pk_mul_f32 v[24:25], v[24:25], v[36:37] op_sel_hi:[1,0]
	v_pk_mul_f32 v[26:27], v[26:27], v[36:37] op_sel_hi:[1,0]
	v_pk_mul_f32 v[28:29], v[28:29], v[36:37] op_sel_hi:[1,0]
	v_pk_mul_f32 v[30:31], v[30:31], v[36:37] op_sel_hi:[1,0]
	v_pk_mul_f32 v[32:33], v[32:33], v[36:37] op_sel_hi:[1,0]
	v_pk_mul_f32 v[34:35], v[34:35], v[36:37] op_sel_hi:[1,0]
	v_pk_mul_f32 v[20:21], v[12:13], v[20:21]
	v_pk_mul_f32 v[22:23], v[14:15], v[22:23]
	v_pk_mul_f32 v[24:25], v[8:9], v[24:25]
	v_pk_mul_f32 v[26:27], v[10:11], v[26:27]
	v_pk_mul_f32 v[28:29], v[4:5], v[28:29]
	v_pk_mul_f32 v[30:31], v[6:7], v[30:31]
	v_pk_mul_f32 v[32:33], v[0:1], v[32:33]
	v_pk_mul_f32 v[34:35], v[2:3], v[34:35]
	v_cvt_pk_bf16_f32 v20, v20, v21
	v_cvt_pk_bf16_f32 v21, v22, v23
	v_cvt_pk_bf16_f32 v22, v24, v25
	v_cvt_pk_bf16_f32 v23, v26, v27
	v_cvt_pk_bf16_f32 v24, v28, v29
	v_cvt_pk_bf16_f32 v25, v30, v31
	v_cvt_pk_bf16_f32 v26, v32, v33
	v_cvt_pk_bf16_f32 v27, v34, v35
	global_store_dwordx2 v[16:17], v[20:21], off
	global_store_dwordx2 v[16:17], v[22:23], off offset:512
	global_store_dwordx2 v[16:17], v[24:25], off offset:1024
	global_store_dwordx2 v[16:17], v[26:27], off offset:1536
	v_lshl_add_u64 v[16:17], v[16:17], 0, s[4:5]
	s_cbranch_scc1 .LBB0_84

.LBB0_448:
	s_or_b64 exec, exec, s[2:3]
	v_bfe_u32 v3, v1, 16, 1
	s_movk_i32 s2, 0x7fff
	v_lshlrev_b32_e32 v2, 3, v4
	v_add3_u32 v1, v1, v3, s2
	ds_write_b16_d16_hi v0, v1 offset:60336
	v_mul_u32_u24_e32 v0, 0x90, v9
	v_lshlrev_b32_e32 v1, 1, v2
	s_waitcnt lgkmcnt(0)
	s_barrier
	v_add3_u32 v12, 0, v0, v1
	ds_read_b128 v[100:103], v10 offset:59904
	ds_read_b128 v[104:107], v10 offset:59968
	ds_read_b128 v[108:111], v10
	ds_read_b128 v[112:115], v10 offset:64
	ds_read_b128 v[14:17], v10 offset:59904
	ds_read_b128 v[0:3], v12 offset:36864
	ds_read_b128 v[18:21], v10 offset:59968
	ds_read_b128 v[4:7], v12 offset:36928
	s_waitcnt lgkmcnt(2)
	v_mfma_f32_16x16x32_bf16 v[0:3], v[14:17], v[0:3], 0
	s_lshl_b32 s2, s4, 2
	s_add_i32 s2, s2, 0
	s_add_i32 s2, s2, 0x19200
	s_waitcnt lgkmcnt(0)
	v_mfma_f32_16x16x32_bf16 v[24:27], v[18:21], v[4:7], v[0:3]
	ds_read_b128 v[28:31], v10
	s_nop 1
	ds_read_b128 v[0:3], v12 offset:57600
	ds_read_b128 v[32:35], v10 offset:64
	ds_read_b128 v[4:7], v12 offset:57664
	s_ashr_i32 s3, s40, 6
	s_waitcnt lgkmcnt(2)
	v_mfma_f32_16x16x32_bf16 v[0:3], v[28:31], v[0:3], 0
	v_readlane_b32 s7, v254, 34
	s_waitcnt lgkmcnt(0)
	v_mfma_f32_16x16x32_bf16 v[36:39], v[32:35], v[4:7], v[0:3]
	s_nop 4
	v_and_b32_e32 v0, 48, v23
	v_add_u32_e32 v4, s2, v0
	v_and_or_b32 v0, v201, 64, v0
	v_lshlrev_b32_e32 v12, 2, v0
	ds_read_b128 v[0:3], v4 offset:512
	ds_read_b128 v[4:7], v4 offset:768
	s_lshl_b32 s2, s3, 4
	s_and_b32 s6, s2, 0xffffffc0
	v_or_b32_e32 v40, s6, v9
	s_waitcnt lgkmcnt(1)
	v_fma_f32 v13, v36, v0, v24
	v_fma_f32 v23, v37, v1, v25
	v_fma_f32 v24, v38, v2, v26
	v_fmac_f32_e32 v27, v39, v3
	v_mad_u64_u32 v[36:37], s[4:5], v40, s84, v[8:9]
	v_mov_b32_e32 v116, v36
	ds_read_b128 v[120:123], v116 offset:20736
	ds_read_b128 v[124:127], v116 offset:20800
	ds_read_b128 v[128:131], v116 offset:41472
	ds_read_b128 v[132:135], v116 offset:41536
	ds_bpermute_b32 v38, v12, v24
	ds_bpermute_b32 v39, v12, v27
	ds_read_b128 v[24:27], v36 offset:18432
	s_waitcnt lgkmcnt(0)
	v_mfma_f32_16x16x32_bf16 v[14:17], v[14:17], v[24:27], 0
	ds_read_b128 v[24:27], v36 offset:18496
	ds_bpermute_b32 v13, v12, v13
	v_max_f32_e32 v4, v4, v4
	s_waitcnt lgkmcnt(1)
	v_mfma_f32_16x16x32_bf16 v[14:17], v[18:21], v[24:27], v[14:17]
	ds_read_b128 v[18:21], v36 offset:39168
	ds_read_b128 v[24:27], v36 offset:39232
	s_waitcnt lgkmcnt(2)
	v_max_f32_e64 v13, |v13|, |v13|
	s_waitcnt lgkmcnt(1)
	v_mfma_f32_16x16x32_bf16 v[18:21], v[28:31], v[18:21], 0
	v_max_f32_e32 v4, v13, v4
	ds_bpermute_b32 v23, v12, v23
	v_lshl_add_u32 v12, v9, 2, s7
	s_waitcnt lgkmcnt(1)
	v_mfma_f32_16x16x32_bf16 v[18:21], v[32:35], v[24:27], v[18:21]
	v_lshl_add_u32 v24, s6, 2, v12
	s_movk_i32 s6, 0x210
	v_mad_u32_u24 v36, v11, s6, v24
	v_max_f32_e32 v5, v5, v5
	v_max_f32_e32 v6, v6, v6
	s_nop 2
	v_fma_f32 v14, v0, v18, v14
	v_div_scale_f32 v13, s[4:5], v4, v4, v14
	v_rcp_f32_e32 v18, v13
	v_max_f32_e32 v7, v7, v7
	v_fmac_f32_e32 v17, v3, v21
	s_or_b32 s2, s2, 48
	v_fma_f32 v25, -v13, v18, 1.0
	v_fmac_f32_e32 v18, v25, v18
	v_div_scale_f32 v25, vcc, v14, v4, v14
	v_mul_f32_e32 v26, v25, v18
	v_fma_f32 v27, -v13, v26, v25
	v_fmac_f32_e32 v26, v27, v18
	v_fma_f32 v13, -v13, v26, v25
	v_div_fmas_f32 v13, v13, v18, v26
	v_div_fixup_f32 v13, v13, v4, v14
	s_waitcnt lgkmcnt(0)
	v_max_f32_e64 v14, |v23|, |v23|
	ds_write_b32 v36, v13
	v_fma_f32 v13, v1, v19, v15
	v_max_f32_e32 v5, v14, v5
	v_div_scale_f32 v14, s[4:5], v5, v5, v13
	v_rcp_f32_e32 v15, v14
	s_nop 0
	v_fma_f32 v18, -v14, v15, 1.0
	v_fmac_f32_e32 v15, v18, v15
	v_div_scale_f32 v18, vcc, v13, v5, v13
	v_mul_f32_e32 v19, v18, v15
	v_fma_f32 v23, -v14, v19, v18
	v_fmac_f32_e32 v19, v23, v15
	v_fma_f32 v14, -v14, v19, v18
	v_div_fmas_f32 v14, v14, v15, v19
	v_div_fixup_f32 v14, v14, v5, v13
	v_mad_u32_u24 v13, v11, s6, s6
	v_add_u32_e32 v23, v24, v13
	v_max_f32_e64 v15, |v38|, |v38|
	ds_write_b32 v23, v14
	v_fma_f32 v14, v2, v20, v16
	v_max_f32_e32 v6, v15, v6
	v_div_scale_f32 v15, s[4:5], v6, v6, v14
	v_rcp_f32_e32 v16, v15
	s_nop 0
	v_fma_f32 v18, -v15, v16, 1.0
	v_fmac_f32_e32 v16, v18, v16
	v_div_scale_f32 v18, vcc, v14, v6, v14
	v_mul_f32_e32 v19, v18, v16
	v_fma_f32 v20, -v15, v19, v18
	v_fmac_f32_e32 v19, v20, v16
	v_fma_f32 v15, -v15, v19, v18
	v_div_fmas_f32 v15, v15, v16, v19
	v_div_fixup_f32 v15, v15, v6, v14
	v_mov_b32_e32 v14, 0x420
	v_mad_u32_u24 v14, v11, s6, v14
	v_add_u32_e32 v37, v24, v14
	ds_write_b32 v37, v15
	v_max_f32_e64 v15, |v39|, |v39|
	v_max_f32_e32 v7, v15, v7
	v_div_scale_f32 v15, s[4:5], v7, v7, v17
	v_rcp_f32_e32 v16, v15
	s_nop 0
	v_fma_f32 v18, -v15, v16, 1.0
	v_fmac_f32_e32 v16, v18, v16
	v_div_scale_f32 v18, vcc, v17, v7, v17
	v_mul_f32_e32 v19, v18, v16
	v_fma_f32 v20, -v15, v19, v18
	v_fmac_f32_e32 v19, v20, v16
	v_fma_f32 v15, -v15, v19, v18
	v_div_fmas_f32 v15, v15, v16, v19
	v_div_fixup_f32 v16, v15, v7, v17
	v_mad_u32_u24 v15, v11, s6, v206
	v_add_u32_e32 v38, v24, v15
	ds_write_b32 v38, v16
	v_or_b32_e32 v16, 16, v40
	v_mad_u64_u32 v[20:21], s[4:5], v16, s84, v[8:9]
	s_waitcnt lgkmcnt(0)
	v_mfma_f32_16x16x32_bf16 v[16:19], v[100:103], v[120:123], 0
	v_mfma_f32_16x16x32_bf16 v[24:27], v[108:111], v[128:131], 0
	v_mfma_f32_16x16x32_bf16 v[16:19], v[104:107], v[124:127], v[16:19]
	v_mfma_f32_16x16x32_bf16 v[24:27], v[112:115], v[132:135], v[24:27]
	ds_read_b128 v[136:139], v116 offset:23040
	ds_read_b128 v[140:143], v116 offset:23104
	ds_read_b128 v[144:147], v116 offset:43776
	ds_read_b128 v[148:151], v116 offset:43840
	s_nop 7
	v_fma_f32 v16, v0, v24, v16
	v_div_scale_f32 v20, s[4:5], v4, v4, v16
	v_rcp_f32_e32 v21, v20
	v_fmac_f32_e32 v19, v3, v27
	v_fma_f32 v24, -v20, v21, 1.0
	v_fmac_f32_e32 v21, v24, v21
	v_div_scale_f32 v24, vcc, v16, v4, v16
	v_mul_f32_e32 v28, v24, v21
	v_fma_f32 v29, -v20, v28, v24
	v_fmac_f32_e32 v28, v29, v21
	v_fma_f32 v20, -v20, v28, v24
	v_div_fmas_f32 v20, v20, v21, v28
	v_div_fixup_f32 v16, v20, v4, v16
	ds_write_b32 v36, v16 offset:64
	v_fma_f32 v16, v1, v25, v17
	v_div_scale_f32 v17, s[4:5], v5, v5, v16
	v_rcp_f32_e32 v20, v17
	s_nop 0
	v_fma_f32 v21, -v17, v20, 1.0
	v_fmac_f32_e32 v20, v21, v20
	v_div_scale_f32 v21, vcc, v16, v5, v16
	v_mul_f32_e32 v24, v21, v20
	v_fma_f32 v25, -v17, v24, v21
	v_fmac_f32_e32 v24, v25, v20
	v_fma_f32 v17, -v17, v24, v21
	v_div_fmas_f32 v17, v17, v20, v24
	v_div_fixup_f32 v16, v17, v5, v16
	ds_write_b32 v23, v16 offset:64
	v_fma_f32 v16, v2, v26, v18
	v_div_scale_f32 v17, s[4:5], v6, v6, v16
	v_rcp_f32_e32 v18, v17
	s_nop 0
	v_fma_f32 v20, -v17, v18, 1.0
	v_fmac_f32_e32 v18, v20, v18
	v_div_scale_f32 v20, vcc, v16, v6, v16
	v_mul_f32_e32 v21, v20, v18
	v_fma_f32 v24, -v17, v21, v20
	v_fmac_f32_e32 v21, v24, v18
	v_fma_f32 v17, -v17, v21, v20
	v_div_fmas_f32 v17, v17, v18, v21
	v_div_fixup_f32 v16, v17, v6, v16
	ds_write_b32 v37, v16 offset:64
	v_div_scale_f32 v16, s[4:5], v7, v7, v19
	v_rcp_f32_e32 v17, v16
	s_nop 0
	v_fma_f32 v18, -v16, v17, 1.0
	v_fmac_f32_e32 v17, v18, v17
	v_div_scale_f32 v18, vcc, v19, v7, v19
	v_mul_f32_e32 v20, v18, v17
	v_fma_f32 v21, -v16, v20, v18
	v_fmac_f32_e32 v20, v21, v17
	v_fma_f32 v16, -v16, v20, v18
	v_div_fmas_f32 v16, v16, v17, v20
	v_div_fixup_f32 v16, v16, v7, v19
	ds_write_b32 v38, v16 offset:64
	v_or_b32_e32 v16, 32, v40
	v_mad_u64_u32 v[20:21], s[4:5], v16, s84, v[8:9]
	v_or_b32_e32 v9, s2, v9
	v_mad_u64_u32 v[8:9], s[4:5], v9, s84, v[8:9]
	s_waitcnt lgkmcnt(0)
	v_mfma_f32_16x16x32_bf16 v[16:19], v[100:103], v[136:139], 0
	v_mfma_f32_16x16x32_bf16 v[24:27], v[108:111], v[144:147], 0
	v_mfma_f32_16x16x32_bf16 v[16:19], v[104:107], v[140:143], v[16:19]
	v_mfma_f32_16x16x32_bf16 v[24:27], v[112:115], v[148:151], v[24:27]
	ds_read_b128 v[120:123], v116 offset:25344
	ds_read_b128 v[124:127], v116 offset:25408
	ds_read_b128 v[128:131], v116 offset:46080
	ds_read_b128 v[132:135], v116 offset:46144
	s_nop 7
	v_fma_f32 v16, v0, v24, v16
	v_div_scale_f32 v20, s[4:5], v4, v4, v16
	v_rcp_f32_e32 v21, v20
	v_fmac_f32_e32 v19, v3, v27
	v_fma_f32 v24, -v20, v21, 1.0
	v_fmac_f32_e32 v21, v24, v21
	v_div_scale_f32 v24, vcc, v16, v4, v16
	v_mul_f32_e32 v28, v24, v21
	v_fma_f32 v29, -v20, v28, v24
	v_fmac_f32_e32 v28, v29, v21
	v_fma_f32 v20, -v20, v28, v24
	v_div_fmas_f32 v20, v20, v21, v28
	v_div_fixup_f32 v16, v20, v4, v16
	ds_write_b32 v36, v16 offset:128
	v_fma_f32 v16, v1, v25, v17
	v_div_scale_f32 v17, s[4:5], v5, v5, v16
	v_rcp_f32_e32 v20, v17
	s_nop 0
	v_fma_f32 v21, -v17, v20, 1.0
	v_fmac_f32_e32 v20, v21, v20
	v_div_scale_f32 v21, vcc, v16, v5, v16
	v_mul_f32_e32 v24, v21, v20
	v_fma_f32 v25, -v17, v24, v21
	v_fmac_f32_e32 v24, v25, v20
	v_fma_f32 v17, -v17, v24, v21
	v_div_fmas_f32 v17, v17, v20, v24
	v_div_fixup_f32 v16, v17, v5, v16
	ds_write_b32 v23, v16 offset:128
	v_fma_f32 v16, v2, v26, v18
	v_div_scale_f32 v17, s[4:5], v6, v6, v16
	v_rcp_f32_e32 v18, v17
	s_nop 0
	v_fma_f32 v20, -v17, v18, 1.0
	v_fmac_f32_e32 v18, v20, v18
	v_div_scale_f32 v20, vcc, v16, v6, v16
	v_mul_f32_e32 v21, v20, v18
	v_fma_f32 v23, -v17, v21, v20
	v_fmac_f32_e32 v21, v23, v18
	v_fma_f32 v17, -v17, v21, v20
	v_div_fmas_f32 v17, v17, v18, v21
	v_div_fixup_f32 v16, v17, v6, v16
	ds_write_b32 v37, v16 offset:128
	v_div_scale_f32 v16, s[4:5], v7, v7, v19
	v_rcp_f32_e32 v17, v16
	s_nop 0
	v_fma_f32 v18, -v16, v17, 1.0
	v_fmac_f32_e32 v17, v18, v17
	v_div_scale_f32 v18, vcc, v19, v7, v19
	v_mul_f32_e32 v20, v18, v17
	v_fma_f32 v21, -v16, v20, v18
	v_fmac_f32_e32 v20, v21, v17
	v_fma_f32 v16, -v16, v20, v18
	v_div_fmas_f32 v16, v16, v17, v20
	v_div_fixup_f32 v16, v16, v7, v19
	ds_write_b32 v38, v16 offset:128
	v_lshl_add_u32 v8, s2, 2, v12
	s_lshl_b32 s2, s3, 3
	s_waitcnt lgkmcnt(0)
	v_mfma_f32_16x16x32_bf16 v[16:19], v[100:103], v[120:123], 0
	v_mfma_f32_16x16x32_bf16 v[24:27], v[108:111], v[128:131], 0
	v_mfma_f32_16x16x32_bf16 v[16:19], v[104:107], v[124:127], v[16:19]
	v_mfma_f32_16x16x32_bf16 v[24:27], v[112:115], v[132:135], v[24:27]
	s_mulk_i32 s3, 0x1080
	s_nop 6
	v_fma_f32 v0, v0, v24, v16
	v_div_scale_f32 v9, s[4:5], v4, v4, v0
	v_rcp_f32_e32 v10, v9
	v_fmac_f32_e32 v19, v3, v27
	v_fma_f32 v12, -v9, v10, 1.0
	v_fmac_f32_e32 v10, v12, v10
	v_div_scale_f32 v12, vcc, v0, v4, v0
	v_mul_f32_e32 v16, v12, v10
	v_fma_f32 v20, -v9, v16, v12
	v_fmac_f32_e32 v16, v20, v10
	v_fma_f32 v9, -v9, v16, v12
	v_div_fmas_f32 v9, v9, v10, v16
	v_div_fixup_f32 v0, v9, v4, v0
	v_mad_u32_u24 v4, v11, s6, v8
	ds_write_b32 v4, v0
	v_fma_f32 v0, v1, v25, v17
	v_div_scale_f32 v1, s[4:5], v5, v5, v0
	v_rcp_f32_e32 v4, v1
	s_nop 0
	v_fma_f32 v9, -v1, v4, 1.0
	v_fmac_f32_e32 v4, v9, v4
	v_div_scale_f32 v9, vcc, v0, v5, v0
	v_mul_f32_e32 v10, v9, v4
	v_fma_f32 v11, -v1, v10, v9
	v_fmac_f32_e32 v10, v11, v4
	v_fma_f32 v1, -v1, v10, v9
	v_div_fmas_f32 v1, v1, v4, v10
	v_div_fixup_f32 v0, v1, v5, v0
	v_add_u32_e32 v1, v8, v13
	ds_write_b32 v1, v0
	v_fma_f32 v0, v2, v26, v18
	v_div_scale_f32 v1, s[4:5], v6, v6, v0
	v_rcp_f32_e32 v2, v1
	s_nop 0
	v_fma_f32 v4, -v1, v2, 1.0
	v_fmac_f32_e32 v2, v4, v2
	v_div_scale_f32 v4, vcc, v0, v6, v0
	v_mul_f32_e32 v5, v4, v2
	v_fma_f32 v9, -v1, v5, v4
	v_fmac_f32_e32 v5, v9, v2
	v_fma_f32 v1, -v1, v5, v4
	v_div_fmas_f32 v1, v1, v2, v5
	v_div_fixup_f32 v0, v1, v6, v0
	v_add_u32_e32 v1, v8, v14
	ds_write_b32 v1, v0
	v_div_scale_f32 v0, s[4:5], v7, v7, v19
	v_rcp_f32_e32 v1, v0
	s_nop 0
	v_fma_f32 v2, -v0, v1, 1.0
	v_fmac_f32_e32 v1, v2, v1
	v_div_scale_f32 v2, vcc, v19, v7, v19
	v_mul_f32_e32 v3, v2, v1
	v_fma_f32 v4, -v0, v3, v2
	v_fmac_f32_e32 v3, v4, v1
	v_fma_f32 v0, -v0, v3, v2
	v_lshlrev_b32_e32 v2, 3, v22
	v_div_fmas_f32 v0, v0, v1, v3
	v_add_u32_e32 v10, s7, v2
	v_div_fixup_f32 v0, v0, v7, v19
	v_add_u32_e32 v1, v8, v15
	v_add_u32_e32 v6, s3, v10
	ds_write_b32 v1, v0
	s_waitcnt lgkmcnt(0)
	s_barrier
	s_add_u32 s4, s34, s2
	s_addc_u32 s5, s35, 0
	s_lshl_b64 s[4:5], s[4:5], 11
	s_lshl_b32 s3, s12, 1
	v_lshl_or_b32 v3, v22, 2, s3
	ds_read_b64 v[48:49], v6
	ds_read_b64 v[50:51], v6 offset:528
	ds_read_b64 v[52:53], v6 offset:1056
	ds_read_b64 v[54:55], v6 offset:1584
	ds_read_b64 v[56:57], v6 offset:2112
	ds_read_b64 v[58:59], v6 offset:2640
	ds_read_b64 v[60:61], v6 offset:3168
	ds_read_b64 v[62:63], v6 offset:3696
	s_add_u32 s98, s24, s4
	s_addc_u32 s99, s25, s5
	s_waitcnt lgkmcnt(0)
	v_pk_mul_f32 v[98:99], v[48:49], v[48:49]
	v_add_f32_e32 v64, v98, v99
	v_pk_mul_f32 v[98:99], v[50:51], v[50:51]
	v_add_f32_e32 v65, v98, v99
	v_pk_mul_f32 v[98:99], v[52:53], v[52:53]
	v_add_f32_e32 v66, v98, v99
	v_pk_mul_f32 v[98:99], v[54:55], v[54:55]
	v_add_f32_e32 v67, v98, v99
	v_pk_mul_f32 v[98:99], v[56:57], v[56:57]
	v_add_f32_e32 v68, v98, v99
	v_pk_mul_f32 v[98:99], v[58:59], v[58:59]
	v_add_f32_e32 v69, v98, v99
	v_pk_mul_f32 v[98:99], v[60:61], v[60:61]
	v_add_f32_e32 v70, v98, v99
	v_pk_mul_f32 v[98:99], v[62:63], v[62:63]
	v_add_f32_e32 v71, v98, v99
	v_add_f32_dpp v72, v64, v64 quad_perm:[1,0,3,2] row_mask:0xf bank_mask:0xf
	v_add_f32_dpp v73, v65, v65 quad_perm:[1,0,3,2] row_mask:0xf bank_mask:0xf
	v_add_f32_dpp v74, v66, v66 quad_perm:[1,0,3,2] row_mask:0xf bank_mask:0xf
	v_add_f32_dpp v75, v67, v67 quad_perm:[1,0,3,2] row_mask:0xf bank_mask:0xf
	v_add_f32_dpp v76, v68, v68 quad_perm:[1,0,3,2] row_mask:0xf bank_mask:0xf
	v_add_f32_dpp v77, v69, v69 quad_perm:[1,0,3,2] row_mask:0xf bank_mask:0xf
	v_add_f32_dpp v78, v70, v70 quad_perm:[1,0,3,2] row_mask:0xf bank_mask:0xf
	v_add_f32_dpp v79, v71, v71 quad_perm:[1,0,3,2] row_mask:0xf bank_mask:0xf
	v_add_f32_dpp v64, v72, v72 quad_perm:[2,3,0,1] row_mask:0xf bank_mask:0xf
	v_add_f32_dpp v65, v73, v73 quad_perm:[2,3,0,1] row_mask:0xf bank_mask:0xf
	v_add_f32_dpp v66, v74, v74 quad_perm:[2,3,0,1] row_mask:0xf bank_mask:0xf
	v_add_f32_dpp v67, v75, v75 quad_perm:[2,3,0,1] row_mask:0xf bank_mask:0xf
	v_add_f32_dpp v68, v76, v76 quad_perm:[2,3,0,1] row_mask:0xf bank_mask:0xf
	v_add_f32_dpp v69, v77, v77 quad_perm:[2,3,0,1] row_mask:0xf bank_mask:0xf
	v_add_f32_dpp v70, v78, v78 quad_perm:[2,3,0,1] row_mask:0xf bank_mask:0xf
	v_add_f32_dpp v71, v79, v79 quad_perm:[2,3,0,1] row_mask:0xf bank_mask:0xf
	v_add_f32_dpp v72, v64, v64 row_half_mirror row_mask:0xf bank_mask:0xf
	v_add_f32_dpp v73, v65, v65 row_half_mirror row_mask:0xf bank_mask:0xf
	v_add_f32_dpp v74, v66, v66 row_half_mirror row_mask:0xf bank_mask:0xf
	v_add_f32_dpp v75, v67, v67 row_half_mirror row_mask:0xf bank_mask:0xf
	v_add_f32_dpp v76, v68, v68 row_half_mirror row_mask:0xf bank_mask:0xf
	v_add_f32_dpp v77, v69, v69 row_half_mirror row_mask:0xf bank_mask:0xf
	v_add_f32_dpp v78, v70, v70 row_half_mirror row_mask:0xf bank_mask:0xf
	v_add_f32_dpp v79, v71, v71 row_half_mirror row_mask:0xf bank_mask:0xf
	v_add_f32_dpp v64, v72, v72 row_mirror row_mask:0xf bank_mask:0xf
	v_add_f32_dpp v65, v73, v73 row_mirror row_mask:0xf bank_mask:0xf
	v_add_f32_dpp v66, v74, v74 row_mirror row_mask:0xf bank_mask:0xf
	v_add_f32_dpp v67, v75, v75 row_mirror row_mask:0xf bank_mask:0xf
	v_add_f32_dpp v68, v76, v76 row_mirror row_mask:0xf bank_mask:0xf
	v_add_f32_dpp v69, v77, v77 row_mirror row_mask:0xf bank_mask:0xf
	v_add_f32_dpp v70, v78, v78 row_mirror row_mask:0xf bank_mask:0xf
	v_add_f32_dpp v71, v79, v79 row_mirror row_mask:0xf bank_mask:0xf
	v_add_f32_dpp v64, v64, v64 row_bcast:15 row_mask:0xa bank_mask:0xf
	v_add_f32_dpp v65, v65, v65 row_bcast:15 row_mask:0xa bank_mask:0xf
	v_add_f32_dpp v66, v66, v66 row_bcast:15 row_mask:0xa bank_mask:0xf
	v_add_f32_dpp v67, v67, v67 row_bcast:15 row_mask:0xa bank_mask:0xf
	v_add_f32_dpp v68, v68, v68 row_bcast:15 row_mask:0xa bank_mask:0xf
	v_add_f32_dpp v69, v69, v69 row_bcast:15 row_mask:0xa bank_mask:0xf
	v_add_f32_dpp v70, v70, v70 row_bcast:15 row_mask:0xa bank_mask:0xf
	v_add_f32_dpp v71, v71, v71 row_bcast:15 row_mask:0xa bank_mask:0xf
	v_add_f32_dpp v64, v64, v64 row_bcast:31 row_mask:0xc bank_mask:0xf
	v_add_f32_dpp v65, v65, v65 row_bcast:31 row_mask:0xc bank_mask:0xf
	v_add_f32_dpp v66, v66, v66 row_bcast:31 row_mask:0xc bank_mask:0xf
	v_add_f32_dpp v67, v67, v67 row_bcast:31 row_mask:0xc bank_mask:0xf
	v_add_f32_dpp v68, v68, v68 row_bcast:31 row_mask:0xc bank_mask:0xf
	v_add_f32_dpp v69, v69, v69 row_bcast:31 row_mask:0xc bank_mask:0xf
	v_add_f32_dpp v70, v70, v70 row_bcast:31 row_mask:0xc bank_mask:0xf
	v_add_f32_dpp v71, v71, v71 row_bcast:31 row_mask:0xc bank_mask:0xf
	v_readlane_b32 s46, v64, 63
	v_readlane_b32 s47, v65, 63
	v_readlane_b32 s48, v66, 63
	v_readlane_b32 s49, v67, 63
	v_readlane_b32 s50, v68, 63
	v_readlane_b32 s51, v69, 63
	v_readlane_b32 s52, v70, 63
	v_readlane_b32 s53, v71, 63
	v_mov_b32_e32 v64, s46
	v_mov_b32_e32 v65, s47
	v_mov_b32_e32 v66, s48
	v_mov_b32_e32 v67, s49
	v_mov_b32_e32 v68, s50
	v_mov_b32_e32 v69, s51
	v_mov_b32_e32 v70, s52
	v_mov_b32_e32 v71, s53
	v_fmamk_f32 v64, v64, 0x3c000000, v195
	v_cmp_gt_f32_e32 vcc, s67, v64
	v_mul_f32_e32 v72, 0x4b800000, v64
	s_nop 0
	v_cndmask_b32_e32 v64, v64, v72, vcc
	v_rsq_f32_e32 v64, v64
	s_nop 0
	v_mul_f32_e32 v72, 0x45800000, v64
	v_cndmask_b32_e32 v64, v64, v72, vcc
	v_fmamk_f32 v65, v65, 0x3c000000, v195
	v_cmp_gt_f32_e32 vcc, s67, v65
	v_mul_f32_e32 v73, 0x4b800000, v65
	s_nop 0
	v_cndmask_b32_e32 v65, v65, v73, vcc
	v_rsq_f32_e32 v65, v65
	s_nop 0
	v_mul_f32_e32 v73, 0x45800000, v65
	v_cndmask_b32_e32 v65, v65, v73, vcc
	v_fmamk_f32 v66, v66, 0x3c000000, v195
	v_cmp_gt_f32_e32 vcc, s67, v66
	v_mul_f32_e32 v74, 0x4b800000, v66
	s_nop 0
	v_cndmask_b32_e32 v66, v66, v74, vcc
	v_rsq_f32_e32 v66, v66
	s_nop 0
	v_mul_f32_e32 v74, 0x45800000, v66
	v_cndmask_b32_e32 v66, v66, v74, vcc
	v_fmamk_f32 v67, v67, 0x3c000000, v195
	v_cmp_gt_f32_e32 vcc, s67, v67
	v_mul_f32_e32 v75, 0x4b800000, v67
	s_nop 0
	v_cndmask_b32_e32 v67, v67, v75, vcc
	v_rsq_f32_e32 v67, v67
	s_nop 0
	v_mul_f32_e32 v75, 0x45800000, v67
	v_cndmask_b32_e32 v67, v67, v75, vcc
	v_fmamk_f32 v68, v68, 0x3c000000, v195
	v_cmp_gt_f32_e32 vcc, s67, v68
	v_mul_f32_e32 v76, 0x4b800000, v68
	s_nop 0
	v_cndmask_b32_e32 v68, v68, v76, vcc
	v_rsq_f32_e32 v68, v68
	s_nop 0
	v_mul_f32_e32 v76, 0x45800000, v68
	v_cndmask_b32_e32 v68, v68, v76, vcc
	v_fmamk_f32 v69, v69, 0x3c000000, v195
	v_cmp_gt_f32_e32 vcc, s67, v69
	v_mul_f32_e32 v77, 0x4b800000, v69
	s_nop 0
	v_cndmask_b32_e32 v69, v69, v77, vcc
	v_rsq_f32_e32 v69, v69
	s_nop 0
	v_mul_f32_e32 v77, 0x45800000, v69
	v_cndmask_b32_e32 v69, v69, v77, vcc
	v_fmamk_f32 v70, v70, 0x3c000000, v195
	v_cmp_gt_f32_e32 vcc, s67, v70
	v_mul_f32_e32 v78, 0x4b800000, v70
	s_nop 0
	v_cndmask_b32_e32 v70, v70, v78, vcc
	v_rsq_f32_e32 v70, v70
	s_nop 0
	v_mul_f32_e32 v78, 0x45800000, v70
	v_cndmask_b32_e32 v70, v70, v78, vcc
	v_fmamk_f32 v71, v71, 0x3c000000, v195
	v_cmp_gt_f32_e32 vcc, s67, v71
	v_mul_f32_e32 v79, 0x4b800000, v71
	s_nop 0
	v_cndmask_b32_e32 v71, v71, v79, vcc
	v_rsq_f32_e32 v71, v71
	s_nop 0
	v_mul_f32_e32 v79, 0x45800000, v71
	v_cndmask_b32_e32 v71, v71, v79, vcc
	s_waitcnt vmcnt(0)
	v_mul_f32_e32 v48, v48, v64
	v_mul_f32_e32 v49, v49, v64
	v_pk_mul_f32 v[48:49], v[234:235], v[48:49]
	v_lshlrev_b32_e32 v72, 16, v224
	v_and_b32_e32 v224, 0xffff0000, v224
	v_mul_f32_e32 v48, v48, v72
	v_mul_f32_e32 v49, v49, v224
	v_cvt_pk_bf16_f32 v72, v48, v49
	global_store_dword v3, v72, s[98:99]
	v_mul_f32_e32 v50, v50, v65
	v_mul_f32_e32 v51, v51, v65
	v_pk_mul_f32 v[50:51], v[234:235], v[50:51]
	v_lshlrev_b32_e32 v73, 16, v225
	v_and_b32_e32 v225, 0xffff0000, v225
	v_mul_f32_e32 v50, v50, v73
	v_mul_f32_e32 v51, v51, v225
	v_cvt_pk_bf16_f32 v73, v50, v51
	global_store_dword v3, v73, s[98:99] offset:2048
	s_add_u32 s98, s98, 0x1000
	s_addc_u32 s99, s99, 0
	v_mul_f32_e32 v52, v52, v66
	v_mul_f32_e32 v53, v53, v66
	v_pk_mul_f32 v[52:53], v[234:235], v[52:53]
	v_lshlrev_b32_e32 v74, 16, v226
	v_and_b32_e32 v226, 0xffff0000, v226
	v_mul_f32_e32 v52, v52, v74
	v_mul_f32_e32 v53, v53, v226
	v_cvt_pk_bf16_f32 v74, v52, v53
	global_store_dword v3, v74, s[98:99]
	v_mul_f32_e32 v54, v54, v67
	v_mul_f32_e32 v55, v55, v67
	v_pk_mul_f32 v[54:55], v[234:235], v[54:55]
	v_lshlrev_b32_e32 v75, 16, v227
	v_and_b32_e32 v227, 0xffff0000, v227
	v_mul_f32_e32 v54, v54, v75
	v_mul_f32_e32 v55, v55, v227
	v_cvt_pk_bf16_f32 v75, v54, v55
	global_store_dword v3, v75, s[98:99] offset:2048
	s_add_u32 s98, s98, 0x1000
	s_addc_u32 s99, s99, 0
	v_mul_f32_e32 v56, v56, v68
	v_mul_f32_e32 v57, v57, v68
	v_pk_mul_f32 v[56:57], v[234:235], v[56:57]
	v_lshlrev_b32_e32 v76, 16, v228
	v_and_b32_e32 v228, 0xffff0000, v228
	v_mul_f32_e32 v56, v56, v76
	v_mul_f32_e32 v57, v57, v228
	v_cvt_pk_bf16_f32 v76, v56, v57
	global_store_dword v3, v76, s[98:99]
	v_mul_f32_e32 v58, v58, v69
	v_mul_f32_e32 v59, v59, v69
	v_pk_mul_f32 v[58:59], v[234:235], v[58:59]
	v_lshlrev_b32_e32 v77, 16, v229
	v_and_b32_e32 v229, 0xffff0000, v229
	v_mul_f32_e32 v58, v58, v77
	v_mul_f32_e32 v59, v59, v229
	v_cvt_pk_bf16_f32 v77, v58, v59
	global_store_dword v3, v77, s[98:99] offset:2048
	s_add_u32 s98, s98, 0x1000
	s_addc_u32 s99, s99, 0
	v_mul_f32_e32 v60, v60, v70
	v_mul_f32_e32 v61, v61, v70
	v_pk_mul_f32 v[60:61], v[234:235], v[60:61]
	v_lshlrev_b32_e32 v78, 16, v230
	v_and_b32_e32 v230, 0xffff0000, v230
	v_mul_f32_e32 v60, v60, v78
	v_mul_f32_e32 v61, v61, v230
	v_cvt_pk_bf16_f32 v78, v60, v61
	global_store_dword v3, v78, s[98:99]
	v_mul_f32_e32 v62, v62, v71
	v_mul_f32_e32 v63, v63, v71
	v_pk_mul_f32 v[62:63], v[234:235], v[62:63]
	v_lshlrev_b32_e32 v79, 16, v231
	v_and_b32_e32 v231, 0xffff0000, v231
	v_mul_f32_e32 v62, v62, v79
	v_mul_f32_e32 v63, v63, v231
	v_cvt_pk_bf16_f32 v79, v62, v63
	global_store_dword v3, v79, s[98:99] offset:2048
	s_add_i32 s39, s39, s71
	s_cmpk_gt_i32 s39, 0x7ff
	s_barrier
	s_cbranch_scc1 .LBB0_494
